# static wave priority 3 (instead of 1) for the leading half of the workgroup
# speedup vs baseline: 1.0039x; 1.0039x over previous
; #define LAS __attribute__((address_space(3)))
; __global__ void __launch_bounds__(512, 2) mega_fwd(Params p) {
;     extern __shared__ __attribute__((aligned(16))) unsigned char lds_raw[];
;     LAS unsigned char* lds = (LAS unsigned char*)lds_raw;
;     const int lo = p.ph_lo, hi = p.ph_hi;
_Z8mega_fwd6Params:
	s_load_dwordx8 s[88:95], s[0:1], 0x80
	v_readfirstlane_b32 s3, v0
	s_lshr_b32 s3, s3, 6
	s_cmp_ge_u32 s3, 4
	s_cbranch_scc1 .Lmy_prio_done
	s_setprio 3
